# diff+NA epilogue z-load de-serialization, NA loop accumulators in place
# speedup vs baseline: 1.0239x; 1.0152x over previous
.LBB0_468:
	v_readlane_b32 s4, v253, 54
	v_readlane_b32 s5, v253, 55
	s_andn2_b64 vcc, exec, s[4:5]
	s_waitcnt lgkmcnt(0)
	s_barrier
	s_cbranch_vccnz .LBB0_455
	ds_read2st64_b32 v[4:5], v2 offset1:1
	ds_read2st64_b32 v[6:7], v2 offset0:2 offset1:3
	ds_read2st64_b32 v[8:9], v2 offset0:4 offset1:5
	ds_read2st64_b32 v[10:11], v2 offset0:6 offset1:7
	ds_read2st64_b32 v[12:13], v2 offset0:8 offset1:9
	ds_read2st64_b32 v[92:93], v2 offset0:10 offset1:11
	ds_read2st64_b32 v[94:95], v2 offset0:12 offset1:13
	ds_read2st64_b32 v[98:99], v2 offset0:14 offset1:15
	ds_read2st64_b32 v[102:103], v2 offset0:16 offset1:17
	ds_read2st64_b32 v[114:115], v2 offset0:18 offset1:19
	ds_read2st64_b32 v[116:117], v2 offset0:20 offset1:21
	ds_read2st64_b32 v[118:119], v2 offset0:22 offset1:23
	ds_read2st64_b32 v[120:121], v2 offset0:24 offset1:25
	ds_read2st64_b32 v[122:123], v2 offset0:26 offset1:27
	ds_read2st64_b32 v[124:125], v2 offset0:28 offset1:29
	ds_read2st64_b32 v[126:127], v2 offset0:30 offset1:31
	ds_read2st64_b32 v[128:129], v2 offset0:32 offset1:33
	ds_read2st64_b32 v[130:131], v2 offset0:34 offset1:35
	ds_read2st64_b32 v[132:133], v2 offset0:36 offset1:37
	ds_read2st64_b32 v[134:135], v2 offset0:38 offset1:39
	ds_read2st64_b32 v[136:137], v2 offset0:40 offset1:41
	ds_read2st64_b32 v[138:139], v2 offset0:42 offset1:43
	ds_read2st64_b32 v[140:141], v2 offset0:44 offset1:45
	ds_read2st64_b32 v[142:143], v2 offset0:46 offset1:47
	ds_read2st64_b32 v[144:145], v2 offset0:56 offset1:57
	ds_read2st64_b32 v[146:147], v2 offset0:58 offset1:59
	ds_read2st64_b32 v[14:15], v2 offset0:60 offset1:61
	ds_read2st64_b32 v[80:81], v2 offset0:62 offset1:63
	ds_read2st64_b32 v[148:149], v2 offset0:48 offset1:49
	ds_read2st64_b32 v[150:151], v2 offset0:50 offset1:51
	ds_read2st64_b32 v[152:153], v2 offset0:52 offset1:53
	ds_read2st64_b32 v[154:155], v2 offset0:54 offset1:55
	s_waitcnt lgkmcnt(14)
	v_pk_fma_f32 v[106:107], v[64:65], v[0:1], v[4:5] op_sel_hi:[1,0,1] neg_lo:[0,0,1] neg_hi:[0,0,1]
	v_lshlrev_b32_e32 v174, 2, v193
	v_pk_fma_f32 v[104:105], v[66:67], v[0:1], v[6:7] op_sel_hi:[1,0,1] neg_lo:[0,0,1] neg_hi:[0,0,1]
	v_pk_mul_f32 v[158:159], v[106:107], v[106:107]
	s_waitcnt lgkmcnt(5)
	v_pk_fma_f32 v[88:89], v[28:29], v[0:1], v[14:15] op_sel_hi:[1,0,1] neg_lo:[0,0,1] neg_hi:[0,0,1]
	s_waitcnt lgkmcnt(4)
	v_pk_fma_f32 v[90:91], v[30:31], v[0:1], v[80:81] op_sel_hi:[1,0,1] neg_lo:[0,0,1] neg_hi:[0,0,1]
	v_pk_mul_f32 v[156:157], v[104:105], v[104:105]
	global_load_dwordx4 v[84:87], v174, s[0:1]
	global_load_dwordx4 v[80:83], v174, s[0:1] offset:32
	v_pk_fma_f32 v[96:97], v[70:71], v[0:1], v[10:11] op_sel_hi:[1,0,1] neg_lo:[0,0,1] neg_hi:[0,0,1]
	v_pk_fma_f32 v[108:109], v[68:69], v[0:1], v[8:9] op_sel_hi:[1,0,1] neg_lo:[0,0,1] neg_hi:[0,0,1]
	v_pk_fma_f32 v[92:93], v[74:75], v[0:1], v[92:93] op_sel_hi:[1,0,1] neg_lo:[0,0,1] neg_hi:[0,0,1]
	v_pk_fma_f32 v[100:101], v[72:73], v[0:1], v[12:13] op_sel_hi:[1,0,1] neg_lo:[0,0,1] neg_hi:[0,0,1]
	v_pk_fma_f32 v[74:75], v[78:79], v[0:1], v[98:99] op_sel_hi:[1,0,1] neg_lo:[0,0,1] neg_hi:[0,0,1]
	v_pk_fma_f32 v[94:95], v[76:77], v[0:1], v[94:95] op_sel_hi:[1,0,1] neg_lo:[0,0,1] neg_hi:[0,0,1]
	v_pk_fma_f32 v[72:73], v[50:51], v[0:1], v[114:115] op_sel_hi:[1,0,1] neg_lo:[0,0,1] neg_hi:[0,0,1]
	v_pk_fma_f32 v[76:77], v[48:49], v[0:1], v[102:103] op_sel_hi:[1,0,1] neg_lo:[0,0,1] neg_hi:[0,0,1]
	v_pk_fma_f32 v[54:55], v[54:55], v[0:1], v[118:119] op_sel_hi:[1,0,1] neg_lo:[0,0,1] neg_hi:[0,0,1]
	v_pk_fma_f32 v[52:53], v[52:53], v[0:1], v[116:117] op_sel_hi:[1,0,1] neg_lo:[0,0,1] neg_hi:[0,0,1]
	v_pk_fma_f32 v[58:59], v[58:59], v[0:1], v[122:123] op_sel_hi:[1,0,1] neg_lo:[0,0,1] neg_hi:[0,0,1]
	v_pk_fma_f32 v[78:79], v[56:57], v[0:1], v[120:121] op_sel_hi:[1,0,1] neg_lo:[0,0,1] neg_hi:[0,0,1]
	v_pk_fma_f32 v[48:49], v[62:63], v[0:1], v[126:127] op_sel_hi:[1,0,1] neg_lo:[0,0,1] neg_hi:[0,0,1]
	v_pk_fma_f32 v[50:51], v[60:61], v[0:1], v[124:125] op_sel_hi:[1,0,1] neg_lo:[0,0,1] neg_hi:[0,0,1]
	v_pk_fma_f32 v[34:35], v[34:35], v[0:1], v[130:131] op_sel_hi:[1,0,1] neg_lo:[0,0,1] neg_hi:[0,0,1]
	v_pk_fma_f32 v[32:33], v[32:33], v[0:1], v[128:129] op_sel_hi:[1,0,1] neg_lo:[0,0,1] neg_hi:[0,0,1]
	v_pk_fma_f32 v[38:39], v[38:39], v[0:1], v[134:135] op_sel_hi:[1,0,1] neg_lo:[0,0,1] neg_hi:[0,0,1]
	v_pk_fma_f32 v[56:57], v[36:37], v[0:1], v[132:133] op_sel_hi:[1,0,1] neg_lo:[0,0,1] neg_hi:[0,0,1]
	v_pk_fma_f32 v[36:37], v[42:43], v[0:1], v[138:139] op_sel_hi:[1,0,1] neg_lo:[0,0,1] neg_hi:[0,0,1]
	v_pk_fma_f32 v[42:43], v[40:41], v[0:1], v[136:137] op_sel_hi:[1,0,1] neg_lo:[0,0,1] neg_hi:[0,0,1]
	v_pk_fma_f32 v[40:41], v[46:47], v[0:1], v[142:143] op_sel_hi:[1,0,1] neg_lo:[0,0,1] neg_hi:[0,0,1]
	v_pk_fma_f32 v[46:47], v[44:45], v[0:1], v[140:141] op_sel_hi:[1,0,1] neg_lo:[0,0,1] neg_hi:[0,0,1]
	s_waitcnt lgkmcnt(2)
	v_pk_fma_f32 v[44:45], v[18:19], v[0:1], v[150:151] op_sel_hi:[1,0,1] neg_lo:[0,0,1] neg_hi:[0,0,1]
	v_pk_fma_f32 v[62:63], v[16:17], v[0:1], v[148:149] op_sel_hi:[1,0,1] neg_lo:[0,0,1] neg_hi:[0,0,1]
	s_waitcnt lgkmcnt(0)
	v_pk_fma_f32 v[60:61], v[22:23], v[0:1], v[154:155] op_sel_hi:[1,0,1] neg_lo:[0,0,1] neg_hi:[0,0,1]
	v_pk_fma_f32 v[98:99], v[20:21], v[0:1], v[152:153] op_sel_hi:[1,0,1] neg_lo:[0,0,1] neg_hi:[0,0,1]
	v_pk_fma_f32 v[26:27], v[26:27], v[0:1], v[146:147] op_sel_hi:[1,0,1] neg_lo:[0,0,1] neg_hi:[0,0,1]
	v_pk_fma_f32 v[102:103], v[24:25], v[0:1], v[144:145] op_sel_hi:[1,0,1] neg_lo:[0,0,1] neg_hi:[0,0,1]
	v_add_f32_e32 v0, v158, v159
	v_add_f32_e32 v0, v0, v156
	v_pk_mul_f32 v[162:163], v[108:109], v[108:109]
	v_add_f32_e32 v0, v0, v157
	v_add_f32_e32 v0, v0, v162
	v_pk_mul_f32 v[160:161], v[96:97], v[96:97]
	v_add_f32_e32 v0, v0, v163
	global_load_dwordx4 v[68:71], v174, s[0:1] offset:64
	global_load_dwordx4 v[64:67], v174, s[0:1] offset:96
	v_add_f32_e32 v0, v0, v160
	v_pk_mul_f32 v[166:167], v[100:101], v[100:101]
	v_add_f32_e32 v0, v0, v161
	v_add_f32_e32 v0, v0, v166
	v_pk_mul_f32 v[164:165], v[92:93], v[92:93]
	v_add_f32_e32 v0, v0, v167
	v_add_f32_e32 v0, v0, v164
	v_pk_mul_f32 v[170:171], v[94:95], v[94:95]
	v_add_f32_e32 v0, v0, v165
	v_add_f32_e32 v0, v0, v170
	v_pk_mul_f32 v[168:169], v[74:75], v[74:75]
	global_load_dwordx4 v[10:13], v174, s[0:1] offset:128
	global_load_dwordx4 v[6:9], v174, s[0:1] offset:160
	v_add_f32_e32 v0, v0, v171
	v_add_f32_e32 v0, v0, v168
	v_pk_mul_f32 v[172:173], v[76:77], v[76:77]
	v_add_f32_e32 v0, v0, v169
	v_add_f32_e32 v0, v0, v172
	v_pk_mul_f32 v[114:115], v[72:73], v[72:73]
	v_add_f32_e32 v0, v0, v173
	v_add_f32_e32 v0, v0, v114
	v_lshlrev_b32_e32 v2, 8, v191
	v_pk_mul_f32 v[116:117], v[52:53], v[52:53]
	v_add_f32_e32 v0, v0, v115
	v_add3_u32 v112, s24, v2, v192
	global_load_dwordx4 v[28:31], v174, s[0:1] offset:192
	global_load_dwordx4 v[2:5], v174, s[0:1] offset:224
	v_add_f32_e32 v0, v0, v116
	v_pk_mul_f32 v[118:119], v[54:55], v[54:55]
	v_add_f32_e32 v0, v0, v117
	v_add_f32_e32 v0, v0, v118
	v_pk_mul_f32 v[120:121], v[78:79], v[78:79]
	v_add_f32_e32 v0, v0, v119
	v_add_f32_e32 v0, v0, v120
	v_pk_mul_f32 v[122:123], v[58:59], v[58:59]
	v_add_f32_e32 v0, v0, v121
	v_add_f32_e32 v0, v0, v122
	v_pk_mul_f32 v[124:125], v[50:51], v[50:51]
	v_add_f32_e32 v0, v0, v123
	v_add_f32_e32 v0, v0, v124
	v_pk_mul_f32 v[126:127], v[48:49], v[48:49]
	v_add_f32_e32 v0, v0, v125
	v_add_f32_e32 v0, v0, v126
	v_pk_mul_f32 v[128:129], v[32:33], v[32:33]
	v_add_f32_e32 v0, v0, v127
	v_add_f32_e32 v0, v0, v128
	v_pk_mul_f32 v[130:131], v[34:35], v[34:35]
	v_add_f32_e32 v0, v0, v129
	v_add_f32_e32 v0, v0, v130
	v_pk_mul_f32 v[132:133], v[56:57], v[56:57]
	v_add_f32_e32 v0, v0, v131
	v_add_f32_e32 v0, v0, v132
	v_pk_mul_f32 v[134:135], v[38:39], v[38:39]
	v_add_f32_e32 v0, v0, v133
	v_add_f32_e32 v0, v0, v134
	v_pk_mul_f32 v[136:137], v[42:43], v[42:43]
	v_add_f32_e32 v0, v0, v135
	v_add_f32_e32 v0, v0, v136
	v_pk_mul_f32 v[138:139], v[36:37], v[36:37]
	v_add_f32_e32 v0, v0, v137
	v_add_f32_e32 v0, v0, v138
	v_pk_mul_f32 v[140:141], v[46:47], v[46:47]
	v_add_f32_e32 v0, v0, v139
	v_add_f32_e32 v0, v0, v140
	v_pk_mul_f32 v[142:143], v[40:41], v[40:41]
	v_add_f32_e32 v0, v0, v141
	v_add_f32_e32 v0, v0, v142
	v_pk_mul_f32 v[16:17], v[62:63], v[62:63]
	v_add_f32_e32 v0, v0, v143
	v_add_f32_e32 v0, v0, v16
	v_pk_mul_f32 v[18:19], v[44:45], v[44:45]
	v_add_f32_e32 v0, v0, v17
	v_add_f32_e32 v0, v0, v18
	v_pk_mul_f32 v[20:21], v[98:99], v[98:99]
	v_add_f32_e32 v0, v0, v19
	v_add_f32_e32 v0, v0, v20
	v_pk_mul_f32 v[22:23], v[60:61], v[60:61]
	v_add_f32_e32 v0, v0, v21
	v_add_f32_e32 v0, v0, v22
	v_pk_mul_f32 v[24:25], v[102:103], v[102:103]
	v_add_f32_e32 v0, v0, v23
	v_add_f32_e32 v0, v0, v24
	v_pk_mul_f32 v[146:147], v[26:27], v[26:27]
	v_add_f32_e32 v0, v0, v25
	v_add_f32_e32 v0, v0, v146
	v_pk_mul_f32 v[14:15], v[88:89], v[88:89]
	v_add_f32_e32 v0, v0, v147
	v_add_f32_e32 v0, v0, v14
	v_pk_mul_f32 v[110:111], v[90:91], v[90:91]
	v_add_f32_e32 v0, v0, v15
	v_add_f32_e32 v0, v0, v110
	v_add_f32_e32 v0, v0, v111
	v_and_b32_e32 v113, 0xf0, v190
	s_movk_i32 s2, 0x50
	ds_bpermute_b32 v110, v184, v0
	v_xad_u32 v180, v113, s2, v112
	s_movk_i32 s2, 0x60
	v_xad_u32 v181, v113, s2, v112
	s_movk_i32 s2, 0x70
	v_xad_u32 v182, v113, s2, v112
	s_movk_i32 s2, 0x80
	v_xad_u32 v183, v113, s2, v112
	s_movk_i32 s2, 0x90
	v_xad_u32 v111, v113, s2, v112
	s_movk_i32 s2, 0xa0
	s_waitcnt lgkmcnt(0)
	v_add_f32_e32 v0, v0, v110
	v_xad_u32 v114, v113, s2, v112
	v_fmamk_f32 v0, v0, 0x3c000000, v213
	s_mov_b32 s2, 0x800000
	v_mul_f32_e32 v110, 0x4b800000, v0
	v_cmp_gt_f32_e32 vcc, s2, v0
	global_load_dwordx4 v[22:25], v174, s[0:1] offset:256
	global_load_dwordx4 v[18:21], v174, s[0:1] offset:288
	v_cndmask_b32_e32 v0, v0, v110, vcc
	v_rsq_f32_e32 v0, v0
	global_load_dwordx4 v[14:17], v174, s[0:1] offset:320
	v_add_u32_e32 v175, v112, v113
	v_xad_u32 v176, v113, 16, v112
	v_mul_f32_e32 v117, 0x45800000, v0
	v_cndmask_b32_e32 v0, v0, v117, vcc
	v_mul_f32_e32 v0, v185, v0
	s_waitcnt vmcnt(10)
	v_pk_mul_f32 v[86:87], v[86:87], v[0:1] op_sel_hi:[1,0]
	v_pk_mul_f32 v[84:85], v[84:85], v[0:1] op_sel_hi:[1,0]
	v_pk_mul_f32 v[86:87], v[104:105], v[86:87]
	v_pk_mul_f32 v[84:85], v[106:107], v[84:85]
	s_waitcnt vmcnt(9)
	v_pk_mul_f32 v[80:81], v[80:81], v[0:1] op_sel_hi:[1,0]
	v_cvt_pk_bf16_f32 v84, v84, v85
	v_cvt_pk_bf16_f32 v85, v86, v87
	v_pk_mul_f32 v[80:81], v[108:109], v[80:81]
	ds_write_b64 v175, v[84:85]
	v_pk_mul_f32 v[84:85], v[82:83], v[0:1] op_sel_hi:[1,0]
	v_cvt_pk_bf16_f32 v86, v80, v81
	global_load_dwordx4 v[80:83], v174, s[0:1] offset:352
	v_pk_mul_f32 v[84:85], v[96:97], v[84:85]
	s_waitcnt vmcnt(9)
	v_pk_mul_f32 v[68:69], v[68:69], v[0:1] op_sel_hi:[1,0]
	v_cvt_pk_bf16_f32 v87, v84, v85
	ds_write_b64 v176, v[86:87]
	v_pk_mul_f32 v[84:85], v[70:71], v[0:1] op_sel_hi:[1,0]
	v_pk_mul_f32 v[86:87], v[100:101], v[68:69]
	global_load_dwordx4 v[68:71], v174, s[0:1] offset:384
	v_pk_mul_f32 v[84:85], v[92:93], v[84:85]
	v_xad_u32 v177, v113, 32, v112
	v_cvt_pk_bf16_f32 v86, v86, v87
	v_cvt_pk_bf16_f32 v87, v84, v85
	ds_write_b64 v177, v[86:87]
	s_waitcnt vmcnt(9)
	v_pk_mul_f32 v[84:85], v[66:67], v[0:1] op_sel_hi:[1,0]
	v_pk_mul_f32 v[86:87], v[64:65], v[0:1] op_sel_hi:[1,0]
	global_load_dwordx4 v[64:67], v174, s[0:1] offset:416
	v_pk_mul_f32 v[86:87], v[94:95], v[86:87]
	v_pk_mul_f32 v[74:75], v[74:75], v[84:85]
	v_xad_u32 v178, v113, 48, v112
	v_cvt_pk_bf16_f32 v86, v86, v87
	v_cvt_pk_bf16_f32 v87, v74, v75
	ds_write_b64 v178, v[86:87]
	s_waitcnt vmcnt(9)
	v_pk_mul_f32 v[12:13], v[12:13], v[0:1] op_sel_hi:[1,0]
	global_load_dwordx4 v[84:87], v174, s[0:1] offset:448
	v_pk_mul_f32 v[10:11], v[10:11], v[0:1] op_sel_hi:[1,0]
	v_pk_mul_f32 v[12:13], v[72:73], v[12:13]
	v_pk_mul_f32 v[10:11], v[76:77], v[10:11]
	v_xad_u32 v179, v113, 64, v112
	v_cvt_pk_bf16_f32 v10, v10, v11
	v_cvt_pk_bf16_f32 v11, v12, v13
	ds_write_b64 v179, v[10:11]
	s_waitcnt vmcnt(9)
	v_pk_mul_f32 v[12:13], v[8:9], v[0:1] op_sel_hi:[1,0]
	global_load_dwordx4 v[8:11], v174, s[0:1] offset:480
	v_pk_mul_f32 v[6:7], v[6:7], v[0:1] op_sel_hi:[1,0]
	v_pk_mul_f32 v[12:13], v[54:55], v[12:13]
	v_pk_mul_f32 v[6:7], v[52:53], v[6:7]
	s_waitcnt vmcnt(8)
	v_pk_mul_f32 v[4:5], v[0:1], v[4:5] op_sel_hi:[0,1]
	v_cvt_pk_bf16_f32 v6, v6, v7
	v_cvt_pk_bf16_f32 v7, v12, v13
	ds_write_b64 v180, v[6:7]
	v_pk_mul_f32 v[6:7], v[30:31], v[0:1] op_sel_hi:[1,0]
	v_pk_mul_f32 v[12:13], v[28:29], v[0:1] op_sel_hi:[1,0]
	v_pk_mul_f32 v[52:53], v[58:59], v[6:7]
	v_pk_mul_f32 v[12:13], v[78:79], v[12:13]
	v_and_b32_e32 v6, 0x78, v189
	v_cvt_pk_bf16_f32 v12, v12, v13
	v_or_b32_e32 v13, s8, v6
	v_or_b32_e32 v6, s7, v188
	v_ashrrev_i32_e32 v7, 31, v6
	v_lshlrev_b64 v[54:55], 11, v[6:7]
	v_lshlrev_b32_e32 v6, 1, v13
	v_or_b32_e32 v54, v54, v6
	v_lshl_add_u64 v[28:29], s[64:65], 0, v[54:55]
	global_load_dwordx4 v[28:31], v[28:29], off nt
	v_pk_mul_f32 v[2:3], v[0:1], v[2:3] op_sel_hi:[0,1]
	v_pk_mul_f32 v[2:3], v[50:51], v[2:3]
	v_pk_mul_f32 v[4:5], v[48:49], v[4:5]
	v_cvt_pk_bf16_f32 v13, v52, v53
	v_cvt_pk_bf16_f32 v2, v2, v3
	v_cvt_pk_bf16_f32 v3, v4, v5
	ds_write_b64 v181, v[12:13]
	ds_write_b64 v182, v[2:3]
	s_waitcnt vmcnt(8)
	v_pk_mul_f32 v[2:3], v[0:1], v[24:25] op_sel_hi:[0,1]
	v_pk_mul_f32 v[4:5], v[0:1], v[22:23] op_sel_hi:[0,1]
	v_pk_mul_f32 v[4:5], v[32:33], v[4:5]
	v_pk_mul_f32 v[2:3], v[34:35], v[2:3]
	v_cvt_pk_bf16_f32 v4, v4, v5
	v_cvt_pk_bf16_f32 v5, v2, v3
	ds_write_b64 v183, v[4:5]
	s_waitcnt vmcnt(7)
	v_pk_mul_f32 v[2:3], v[0:1], v[20:21] op_sel_hi:[0,1]
	v_pk_mul_f32 v[4:5], v[0:1], v[18:19] op_sel_hi:[0,1]
	v_pk_mul_f32 v[4:5], v[56:57], v[4:5]
	v_pk_mul_f32 v[2:3], v[38:39], v[2:3]
	v_cvt_pk_bf16_f32 v4, v4, v5
	v_cvt_pk_bf16_f32 v5, v2, v3
	ds_write_b64 v111, v[4:5]
	s_waitcnt vmcnt(6)
	v_pk_mul_f32 v[2:3], v[0:1], v[16:17] op_sel_hi:[0,1]
	v_pk_mul_f32 v[4:5], v[0:1], v[14:15] op_sel_hi:[0,1]
	v_pk_mul_f32 v[4:5], v[42:43], v[4:5]
	v_pk_mul_f32 v[2:3], v[36:37], v[2:3]
	v_cvt_pk_bf16_f32 v4, v4, v5
	v_cvt_pk_bf16_f32 v5, v2, v3
	ds_write_b64 v114, v[4:5]
	s_waitcnt vmcnt(5)
	v_pk_mul_f32 v[2:3], v[0:1], v[82:83] op_sel_hi:[0,1]
	v_pk_mul_f32 v[4:5], v[0:1], v[80:81] op_sel_hi:[0,1]
	s_movk_i32 s2, 0xb0
	v_pk_mul_f32 v[4:5], v[46:47], v[4:5]
	v_pk_mul_f32 v[2:3], v[40:41], v[2:3]
	v_xad_u32 v110, v113, s2, v112
	v_cvt_pk_bf16_f32 v4, v4, v5
	v_cvt_pk_bf16_f32 v5, v2, v3
	ds_write_b64 v110, v[4:5]
	s_waitcnt vmcnt(4)
	v_pk_mul_f32 v[2:3], v[0:1], v[70:71] op_sel_hi:[0,1]
	v_pk_mul_f32 v[4:5], v[0:1], v[68:69] op_sel_hi:[0,1]
	s_movk_i32 s2, 0xc0
	v_pk_mul_f32 v[4:5], v[62:63], v[4:5]
	v_pk_mul_f32 v[2:3], v[44:45], v[2:3]
	v_xad_u32 v115, v113, s2, v112
	v_cvt_pk_bf16_f32 v4, v4, v5
	v_cvt_pk_bf16_f32 v5, v2, v3
	ds_write_b64 v115, v[4:5]
	s_waitcnt vmcnt(3)
	v_pk_mul_f32 v[2:3], v[0:1], v[66:67] op_sel_hi:[0,1]
	v_pk_mul_f32 v[4:5], v[0:1], v[64:65] op_sel_hi:[0,1]
	s_movk_i32 s2, 0xd0
	v_pk_mul_f32 v[4:5], v[98:99], v[4:5]
	v_pk_mul_f32 v[2:3], v[60:61], v[2:3]
	v_xad_u32 v116, v113, s2, v112
	v_cvt_pk_bf16_f32 v4, v4, v5
	v_cvt_pk_bf16_f32 v5, v2, v3
	ds_write_b64 v116, v[4:5]
	s_waitcnt vmcnt(2)
	v_pk_mul_f32 v[2:3], v[0:1], v[86:87] op_sel_hi:[0,1]
	v_pk_mul_f32 v[4:5], v[0:1], v[84:85] op_sel_hi:[0,1]
	v_pk_mul_f32 v[4:5], v[102:103], v[4:5]
	v_pk_mul_f32 v[2:3], v[26:27], v[2:3]
	s_movk_i32 s2, 0xe0
	v_cvt_pk_bf16_f32 v4, v4, v5
	v_cvt_pk_bf16_f32 v5, v2, v3
	v_xad_u32 v2, v113, s2, v112
	ds_write_b64 v2, v[4:5]
	s_waitcnt vmcnt(1)
	v_pk_mul_f32 v[2:3], v[0:1], v[10:11] op_sel_hi:[0,1]
	v_pk_mul_f32 v[4:5], v[0:1], v[8:9] op_sel_hi:[0,1]
	v_pk_mul_f32 v[4:5], v[88:89], v[4:5]
	v_pk_mul_f32 v[2:3], v[90:91], v[2:3]
	v_cvt_pk_bf16_f32 v4, v4, v5
	v_cvt_pk_bf16_f32 v5, v2, v3
	s_movk_i32 s2, 0xf0
	v_xad_u32 v0, v113, s2, v112
	ds_write_b64 v0, v[4:5]
	v_or_b32_e32 v116, 4, v188
	v_or_b32_e32 v2, s7, v116
	v_ashrrev_i32_e32 v3, 31, v2
	v_lshlrev_b64 v[68:69], 11, v[2:3]
	v_or_b32_e32 v68, v68, v6
	v_lshl_add_u64 v[2:3], s[64:65], 0, v[68:69]
	global_load_dwordx4 v[32:35], v[2:3], off nt
	v_or_b32_e32 v116, 8, v188
	v_or_b32_e32 v2, s7, v116
	v_ashrrev_i32_e32 v3, 31, v2
	v_lshlrev_b64 v[70:71], 11, v[2:3]
	v_or_b32_e32 v70, v70, v6
	v_lshl_add_u64 v[2:3], s[64:65], 0, v[70:71]
	global_load_dwordx4 v[36:39], v[2:3], off nt
	v_or_b32_e32 v116, 12, v188
	v_or_b32_e32 v2, s7, v116
	v_ashrrev_i32_e32 v3, 31, v2
	v_lshlrev_b64 v[72:73], 11, v[2:3]
	v_or_b32_e32 v72, v72, v6
	v_lshl_add_u64 v[2:3], s[64:65], 0, v[72:73]
	global_load_dwordx4 v[40:43], v[2:3], off nt
	v_or_b32_e32 v116, 16, v188
	v_or_b32_e32 v2, s7, v116
	v_ashrrev_i32_e32 v3, 31, v2
	v_lshlrev_b64 v[74:75], 11, v[2:3]
	v_or_b32_e32 v74, v74, v6
	v_lshl_add_u64 v[2:3], s[64:65], 0, v[74:75]
	global_load_dwordx4 v[44:47], v[2:3], off nt
	v_or_b32_e32 v116, 20, v188
	v_or_b32_e32 v2, s7, v116
	v_ashrrev_i32_e32 v3, 31, v2
	v_lshlrev_b64 v[76:77], 11, v[2:3]
	v_or_b32_e32 v76, v76, v6
	v_lshl_add_u64 v[2:3], s[64:65], 0, v[76:77]
	global_load_dwordx4 v[48:51], v[2:3], off nt
	v_or_b32_e32 v116, 24, v188
	v_or_b32_e32 v2, s7, v116
	v_ashrrev_i32_e32 v3, 31, v2
	v_lshlrev_b64 v[78:79], 11, v[2:3]
	v_or_b32_e32 v78, v78, v6
	v_lshl_add_u64 v[2:3], s[64:65], 0, v[78:79]
	global_load_dwordx4 v[60:63], v[2:3], off nt
	v_or_b32_e32 v116, 28, v188
	v_or_b32_e32 v2, s7, v116
	v_ashrrev_i32_e32 v3, 31, v2
	v_lshlrev_b64 v[80:81], 11, v[2:3]
	v_or_b32_e32 v80, v80, v6
	v_lshl_add_u64 v[2:3], s[64:65], 0, v[80:81]
	global_load_dwordx4 v[64:67], v[2:3], off nt
	v_or_b32_e32 v116, 0, v188
	v_xor_b32_e32 v2, v116, v187
	v_lshlrev_b32_e32 v2, 4, v2
	v_and_b32_e32 v2, 0xf0, v2
	v_lshlrev_b32_e32 v3, 8, v116
	v_add3_u32 v3, s24, v3, v2
	ds_read_b128 v[84:87], v3
	v_or_b32_e32 v116, 4, v188
	v_xor_b32_e32 v2, v116, v187
	v_lshlrev_b32_e32 v2, 4, v2
	v_and_b32_e32 v2, 0xf0, v2
	v_lshlrev_b32_e32 v3, 8, v116
	v_add3_u32 v3, s24, v3, v2
	ds_read_b128 v[88:91], v3
	v_or_b32_e32 v116, 8, v188
	v_xor_b32_e32 v2, v116, v187
	v_lshlrev_b32_e32 v2, 4, v2
	v_and_b32_e32 v2, 0xf0, v2
	v_lshlrev_b32_e32 v3, 8, v116
	v_add3_u32 v3, s24, v3, v2
	ds_read_b128 v[92:95], v3
	v_or_b32_e32 v116, 12, v188
	v_xor_b32_e32 v2, v116, v187
	v_lshlrev_b32_e32 v2, 4, v2
	v_and_b32_e32 v2, 0xf0, v2
	v_lshlrev_b32_e32 v3, 8, v116
	v_add3_u32 v3, s24, v3, v2
	ds_read_b128 v[96:99], v3
	v_or_b32_e32 v116, 16, v188
	v_xor_b32_e32 v2, v116, v187
	v_lshlrev_b32_e32 v2, 4, v2
	v_and_b32_e32 v2, 0xf0, v2
	v_lshlrev_b32_e32 v3, 8, v116
	v_add3_u32 v3, s24, v3, v2
	ds_read_b128 v[100:103], v3
	v_or_b32_e32 v116, 20, v188
	v_xor_b32_e32 v2, v116, v187
	v_lshlrev_b32_e32 v2, 4, v2
	v_and_b32_e32 v2, 0xf0, v2
	v_lshlrev_b32_e32 v3, 8, v116
	v_add3_u32 v3, s24, v3, v2
	ds_read_b128 v[104:107], v3
	v_or_b32_e32 v116, 24, v188
	v_xor_b32_e32 v2, v116, v187
	v_lshlrev_b32_e32 v2, 4, v2
	v_and_b32_e32 v2, 0xf0, v2
	v_lshlrev_b32_e32 v3, 8, v116
	v_add3_u32 v3, s24, v3, v2
	ds_read_b128 v[108:111], v3
	v_or_b32_e32 v116, 28, v188
	v_xor_b32_e32 v2, v116, v187
	v_lshlrev_b32_e32 v2, 4, v2
	v_and_b32_e32 v2, 0xf0, v2
	v_lshlrev_b32_e32 v3, 8, v116
	v_add3_u32 v3, s24, v3, v2
	ds_read_b128 v[112:115], v3
	s_waitcnt vmcnt(7) lgkmcnt(7)
	v_lshlrev_b32_e32 v8, 16, v84
	v_and_b32_e32 v9, 0xffff0000, v84
	v_lshlrev_b32_e32 v10, 16, v28
	v_and_b32_e32 v11, 0xffff0000, v28
	v_lshlrev_b32_e32 v12, 16, v85
	v_and_b32_e32 v13, 0xffff0000, v85
	v_lshlrev_b32_e32 v14, 16, v29
	v_and_b32_e32 v15, 0xffff0000, v29
	v_lshlrev_b32_e32 v16, 16, v86
	v_and_b32_e32 v17, 0xffff0000, v86
	v_lshlrev_b32_e32 v18, 16, v30
	v_and_b32_e32 v19, 0xffff0000, v30
	v_lshlrev_b32_e32 v20, 16, v87
	v_and_b32_e32 v21, 0xffff0000, v87
	v_lshlrev_b32_e32 v22, 16, v31
	v_and_b32_e32 v23, 0xffff0000, v31
	v_pk_mul_f32 v[8:9], v[8:9], v[10:11]
	v_pk_mul_f32 v[12:13], v[12:13], v[14:15]
	v_pk_mul_f32 v[16:17], v[16:17], v[18:19]
	v_pk_mul_f32 v[20:21], v[20:21], v[22:23]
	v_cvt_pk_bf16_f32 v84, v8, v9
	v_cvt_pk_bf16_f32 v85, v12, v13
	v_cvt_pk_bf16_f32 v86, v16, v17
	v_cvt_pk_bf16_f32 v87, v20, v21
	v_lshl_add_u64 v[2:3], s[66:67], 0, v[54:55]
	global_store_dwordx4 v[2:3], v[84:87], off nt
	s_waitcnt vmcnt(7) lgkmcnt(6)
	v_lshlrev_b32_e32 v8, 16, v88
	v_and_b32_e32 v9, 0xffff0000, v88
	v_lshlrev_b32_e32 v10, 16, v32
	v_and_b32_e32 v11, 0xffff0000, v32
	v_lshlrev_b32_e32 v12, 16, v89
	v_and_b32_e32 v13, 0xffff0000, v89
	v_lshlrev_b32_e32 v14, 16, v33
	v_and_b32_e32 v15, 0xffff0000, v33
	v_lshlrev_b32_e32 v16, 16, v90
	v_and_b32_e32 v17, 0xffff0000, v90
	v_lshlrev_b32_e32 v18, 16, v34
	v_and_b32_e32 v19, 0xffff0000, v34
	v_lshlrev_b32_e32 v20, 16, v91
	v_and_b32_e32 v21, 0xffff0000, v91
	v_lshlrev_b32_e32 v22, 16, v35
	v_and_b32_e32 v23, 0xffff0000, v35
	v_pk_mul_f32 v[8:9], v[8:9], v[10:11]
	v_pk_mul_f32 v[12:13], v[12:13], v[14:15]
	v_pk_mul_f32 v[16:17], v[16:17], v[18:19]
	v_pk_mul_f32 v[20:21], v[20:21], v[22:23]
	v_cvt_pk_bf16_f32 v88, v8, v9
	v_cvt_pk_bf16_f32 v89, v12, v13
	v_cvt_pk_bf16_f32 v90, v16, v17
	v_cvt_pk_bf16_f32 v91, v20, v21
	v_lshl_add_u64 v[2:3], s[66:67], 0, v[68:69]
	global_store_dwordx4 v[2:3], v[88:91], off nt
	s_waitcnt vmcnt(7) lgkmcnt(5)
	v_lshlrev_b32_e32 v8, 16, v92
	v_and_b32_e32 v9, 0xffff0000, v92
	v_lshlrev_b32_e32 v10, 16, v36
	v_and_b32_e32 v11, 0xffff0000, v36
	v_lshlrev_b32_e32 v12, 16, v93
	v_and_b32_e32 v13, 0xffff0000, v93
	v_lshlrev_b32_e32 v14, 16, v37
	v_and_b32_e32 v15, 0xffff0000, v37
	v_lshlrev_b32_e32 v16, 16, v94
	v_and_b32_e32 v17, 0xffff0000, v94
	v_lshlrev_b32_e32 v18, 16, v38
	v_and_b32_e32 v19, 0xffff0000, v38
	v_lshlrev_b32_e32 v20, 16, v95
	v_and_b32_e32 v21, 0xffff0000, v95
	v_lshlrev_b32_e32 v22, 16, v39
	v_and_b32_e32 v23, 0xffff0000, v39
	v_pk_mul_f32 v[8:9], v[8:9], v[10:11]
	v_pk_mul_f32 v[12:13], v[12:13], v[14:15]
	v_pk_mul_f32 v[16:17], v[16:17], v[18:19]
	v_pk_mul_f32 v[20:21], v[20:21], v[22:23]
	v_cvt_pk_bf16_f32 v92, v8, v9
	v_cvt_pk_bf16_f32 v93, v12, v13
	v_cvt_pk_bf16_f32 v94, v16, v17
	v_cvt_pk_bf16_f32 v95, v20, v21
	v_lshl_add_u64 v[2:3], s[66:67], 0, v[70:71]
	global_store_dwordx4 v[2:3], v[92:95], off nt
	s_waitcnt vmcnt(7) lgkmcnt(4)
	v_lshlrev_b32_e32 v8, 16, v96
	v_and_b32_e32 v9, 0xffff0000, v96
	v_lshlrev_b32_e32 v10, 16, v40
	v_and_b32_e32 v11, 0xffff0000, v40
	v_lshlrev_b32_e32 v12, 16, v97
	v_and_b32_e32 v13, 0xffff0000, v97
	v_lshlrev_b32_e32 v14, 16, v41
	v_and_b32_e32 v15, 0xffff0000, v41
	v_lshlrev_b32_e32 v16, 16, v98
	v_and_b32_e32 v17, 0xffff0000, v98
	v_lshlrev_b32_e32 v18, 16, v42
	v_and_b32_e32 v19, 0xffff0000, v42
	v_lshlrev_b32_e32 v20, 16, v99
	v_and_b32_e32 v21, 0xffff0000, v99
	v_lshlrev_b32_e32 v22, 16, v43
	v_and_b32_e32 v23, 0xffff0000, v43
	v_pk_mul_f32 v[8:9], v[8:9], v[10:11]
	v_pk_mul_f32 v[12:13], v[12:13], v[14:15]
	v_pk_mul_f32 v[16:17], v[16:17], v[18:19]
	v_pk_mul_f32 v[20:21], v[20:21], v[22:23]
	v_cvt_pk_bf16_f32 v96, v8, v9
	v_cvt_pk_bf16_f32 v97, v12, v13
	v_cvt_pk_bf16_f32 v98, v16, v17
	v_cvt_pk_bf16_f32 v99, v20, v21
	v_lshl_add_u64 v[2:3], s[66:67], 0, v[72:73]
	global_store_dwordx4 v[2:3], v[96:99], off nt
	s_waitcnt vmcnt(7) lgkmcnt(3)
	v_lshlrev_b32_e32 v8, 16, v100
	v_and_b32_e32 v9, 0xffff0000, v100
	v_lshlrev_b32_e32 v10, 16, v44
	v_and_b32_e32 v11, 0xffff0000, v44
	v_lshlrev_b32_e32 v12, 16, v101
	v_and_b32_e32 v13, 0xffff0000, v101
	v_lshlrev_b32_e32 v14, 16, v45
	v_and_b32_e32 v15, 0xffff0000, v45
	v_lshlrev_b32_e32 v16, 16, v102
	v_and_b32_e32 v17, 0xffff0000, v102
	v_lshlrev_b32_e32 v18, 16, v46
	v_and_b32_e32 v19, 0xffff0000, v46
	v_lshlrev_b32_e32 v20, 16, v103
	v_and_b32_e32 v21, 0xffff0000, v103
	v_lshlrev_b32_e32 v22, 16, v47
	v_and_b32_e32 v23, 0xffff0000, v47
	v_pk_mul_f32 v[8:9], v[8:9], v[10:11]
	v_pk_mul_f32 v[12:13], v[12:13], v[14:15]
	v_pk_mul_f32 v[16:17], v[16:17], v[18:19]
	v_pk_mul_f32 v[20:21], v[20:21], v[22:23]
	v_cvt_pk_bf16_f32 v100, v8, v9
	v_cvt_pk_bf16_f32 v101, v12, v13
	v_cvt_pk_bf16_f32 v102, v16, v17
	v_cvt_pk_bf16_f32 v103, v20, v21
	v_lshl_add_u64 v[2:3], s[66:67], 0, v[74:75]
	global_store_dwordx4 v[2:3], v[100:103], off nt
	s_waitcnt vmcnt(7) lgkmcnt(2)
	v_lshlrev_b32_e32 v8, 16, v104
	v_and_b32_e32 v9, 0xffff0000, v104
	v_lshlrev_b32_e32 v10, 16, v48
	v_and_b32_e32 v11, 0xffff0000, v48
	v_lshlrev_b32_e32 v12, 16, v105
	v_and_b32_e32 v13, 0xffff0000, v105
	v_lshlrev_b32_e32 v14, 16, v49
	v_and_b32_e32 v15, 0xffff0000, v49
	v_lshlrev_b32_e32 v16, 16, v106
	v_and_b32_e32 v17, 0xffff0000, v106
	v_lshlrev_b32_e32 v18, 16, v50
	v_and_b32_e32 v19, 0xffff0000, v50
	v_lshlrev_b32_e32 v20, 16, v107
	v_and_b32_e32 v21, 0xffff0000, v107
	v_lshlrev_b32_e32 v22, 16, v51
	v_and_b32_e32 v23, 0xffff0000, v51
	v_pk_mul_f32 v[8:9], v[8:9], v[10:11]
	v_pk_mul_f32 v[12:13], v[12:13], v[14:15]
	v_pk_mul_f32 v[16:17], v[16:17], v[18:19]
	v_pk_mul_f32 v[20:21], v[20:21], v[22:23]
	v_cvt_pk_bf16_f32 v104, v8, v9
	v_cvt_pk_bf16_f32 v105, v12, v13
	v_cvt_pk_bf16_f32 v106, v16, v17
	v_cvt_pk_bf16_f32 v107, v20, v21
	v_lshl_add_u64 v[2:3], s[66:67], 0, v[76:77]
	global_store_dwordx4 v[2:3], v[104:107], off nt
	s_waitcnt vmcnt(7) lgkmcnt(1)
	v_lshlrev_b32_e32 v8, 16, v108
	v_and_b32_e32 v9, 0xffff0000, v108
	v_lshlrev_b32_e32 v10, 16, v60
	v_and_b32_e32 v11, 0xffff0000, v60
	v_lshlrev_b32_e32 v12, 16, v109
	v_and_b32_e32 v13, 0xffff0000, v109
	v_lshlrev_b32_e32 v14, 16, v61
	v_and_b32_e32 v15, 0xffff0000, v61
	v_lshlrev_b32_e32 v16, 16, v110
	v_and_b32_e32 v17, 0xffff0000, v110
	v_lshlrev_b32_e32 v18, 16, v62
	v_and_b32_e32 v19, 0xffff0000, v62
	v_lshlrev_b32_e32 v20, 16, v111
	v_and_b32_e32 v21, 0xffff0000, v111
	v_lshlrev_b32_e32 v22, 16, v63
	v_and_b32_e32 v23, 0xffff0000, v63
	v_pk_mul_f32 v[8:9], v[8:9], v[10:11]
	v_pk_mul_f32 v[12:13], v[12:13], v[14:15]
	v_pk_mul_f32 v[16:17], v[16:17], v[18:19]
	v_pk_mul_f32 v[20:21], v[20:21], v[22:23]
	v_cvt_pk_bf16_f32 v108, v8, v9
	v_cvt_pk_bf16_f32 v109, v12, v13
	v_cvt_pk_bf16_f32 v110, v16, v17
	v_cvt_pk_bf16_f32 v111, v20, v21
	v_lshl_add_u64 v[2:3], s[66:67], 0, v[78:79]
	global_store_dwordx4 v[2:3], v[108:111], off nt
	s_waitcnt vmcnt(7) lgkmcnt(0)
	v_lshlrev_b32_e32 v8, 16, v112
	v_and_b32_e32 v9, 0xffff0000, v112
	v_lshlrev_b32_e32 v10, 16, v64
	v_and_b32_e32 v11, 0xffff0000, v64
	v_lshlrev_b32_e32 v12, 16, v113
	v_and_b32_e32 v13, 0xffff0000, v113
	v_lshlrev_b32_e32 v14, 16, v65
	v_and_b32_e32 v15, 0xffff0000, v65
	v_lshlrev_b32_e32 v16, 16, v114
	v_and_b32_e32 v17, 0xffff0000, v114
	v_lshlrev_b32_e32 v18, 16, v66
	v_and_b32_e32 v19, 0xffff0000, v66
	v_lshlrev_b32_e32 v20, 16, v115
	v_and_b32_e32 v21, 0xffff0000, v115
	v_lshlrev_b32_e32 v22, 16, v67
	v_and_b32_e32 v23, 0xffff0000, v67
	v_pk_mul_f32 v[8:9], v[8:9], v[10:11]
	v_pk_mul_f32 v[12:13], v[12:13], v[14:15]
	v_pk_mul_f32 v[16:17], v[16:17], v[18:19]
	v_pk_mul_f32 v[20:21], v[20:21], v[22:23]
	v_cvt_pk_bf16_f32 v112, v8, v9
	v_cvt_pk_bf16_f32 v113, v12, v13
	v_cvt_pk_bf16_f32 v114, v16, v17
	v_cvt_pk_bf16_f32 v115, v20, v21
	v_lshl_add_u64 v[2:3], s[66:67], 0, v[80:81]
	global_store_dwordx4 v[2:3], v[112:115], off nt
	s_branch .LBB0_455

.LBB0_490:
	v_div_scale_f32 v0, s[0:1], v160, v160, 1.0
	v_rcp_f32_e32 v2, v0
	v_readlane_b32 s0, v254, 4
	v_lshlrev_b32_e32 v7, 4, v230
	s_waitcnt vmcnt(0) lgkmcnt(0)
	s_barrier
	v_fma_f32 v3, -v0, v2, 1.0
	v_fmac_f32_e32 v2, v3, v2
	v_div_scale_f32 v3, vcc, 1.0, v160, 1.0
	v_mul_f32_e32 v4, v3, v2
	v_fma_f32 v5, -v0, v4, v3
	v_fmac_f32_e32 v4, v5, v2
	v_fma_f32 v0, -v0, v4, v3
	v_div_fmas_f32 v0, v0, v2, v4
	v_div_fixup_f32 v0, v0, v160, 1.0
	v_add3_u32 v6, s0, v235, v234
	v_pk_mul_f32 v[2:3], v[80:81], v[0:1] op_sel_hi:[1,0]
	v_pk_mul_f32 v[4:5], v[82:83], v[0:1] op_sel_hi:[1,0]
	v_cvt_pk_bf16_f32 v2, v2, v3
	v_cvt_pk_bf16_f32 v3, v4, v5
	v_add_u32_e32 v4, v6, v7
	ds_write_b64 v4, v[2:3] offset:32768
	v_pk_mul_f32 v[2:3], v[84:85], v[0:1] op_sel_hi:[1,0]
	v_pk_mul_f32 v[4:5], v[86:87], v[0:1] op_sel_hi:[1,0]
	v_cvt_pk_bf16_f32 v2, v2, v3
	v_cvt_pk_bf16_f32 v3, v4, v5
	v_xad_u32 v4, v7, 16, v6
	ds_write_b64 v4, v[2:3] offset:32768
	v_pk_mul_f32 v[2:3], v[88:89], v[0:1] op_sel_hi:[1,0]
	v_pk_mul_f32 v[4:5], v[90:91], v[0:1] op_sel_hi:[1,0]
	v_cvt_pk_bf16_f32 v2, v2, v3
	v_cvt_pk_bf16_f32 v3, v4, v5
	v_xad_u32 v4, v7, 32, v6
	ds_write_b64 v4, v[2:3] offset:32768
	v_pk_mul_f32 v[2:3], v[92:93], v[0:1] op_sel_hi:[1,0]
	v_pk_mul_f32 v[4:5], v[94:95], v[0:1] op_sel_hi:[1,0]
	v_cvt_pk_bf16_f32 v2, v2, v3
	v_cvt_pk_bf16_f32 v3, v4, v5
	v_xad_u32 v4, v7, 48, v6
	ds_write_b64 v4, v[2:3] offset:32768
	v_pk_mul_f32 v[2:3], v[96:97], v[0:1] op_sel_hi:[1,0]
	v_pk_mul_f32 v[4:5], v[98:99], v[0:1] op_sel_hi:[1,0]
	v_cvt_pk_bf16_f32 v2, v2, v3
	v_cvt_pk_bf16_f32 v3, v4, v5
	v_xad_u32 v4, v7, 64, v6
	ds_write_b64 v4, v[2:3] offset:32768
	v_pk_mul_f32 v[2:3], v[100:101], v[0:1] op_sel_hi:[1,0]
	v_pk_mul_f32 v[4:5], v[102:103], v[0:1] op_sel_hi:[1,0]
	s_movk_i32 s1, 0x50
	v_cvt_pk_bf16_f32 v2, v2, v3
	v_cvt_pk_bf16_f32 v3, v4, v5
	v_xad_u32 v4, v7, s1, v6
	ds_write_b64 v4, v[2:3] offset:32768
	v_pk_mul_f32 v[2:3], v[104:105], v[0:1] op_sel_hi:[1,0]
	v_pk_mul_f32 v[4:5], v[106:107], v[0:1] op_sel_hi:[1,0]
	s_movk_i32 s1, 0x60
	v_cvt_pk_bf16_f32 v2, v2, v3
	v_cvt_pk_bf16_f32 v3, v4, v5
	v_xad_u32 v4, v7, s1, v6
	ds_write_b64 v4, v[2:3] offset:32768
	v_pk_mul_f32 v[2:3], v[108:109], v[0:1] op_sel_hi:[1,0]
	v_pk_mul_f32 v[4:5], v[110:111], v[0:1] op_sel_hi:[1,0]
	s_movk_i32 s1, 0x70
	v_cvt_pk_bf16_f32 v2, v2, v3
	v_cvt_pk_bf16_f32 v3, v4, v5
	v_xad_u32 v0, v7, s1, v6
	ds_write_b64 v0, v[2:3] offset:32768
	v_lshrrev_b32_e32 v0, 3, v231
	v_xor_b32_e32 v2, v0, v230
	v_lshl_add_u32 v6, v2, 4, s0
	v_readlane_b32 s0, v254, 1
	s_or_b32 s0, s30, s0
	v_readlane_b32 s1, v254, 7
	s_add_i32 s1, s0, s1
	v_readlane_b32 s2, v254, 8
	s_add_i32 s2, s0, s2
	v_lshl_or_b32 v7, s19, 7, v7
	v_or_b32_e32 v14, 8, v0
	v_or_b32_e32 v8, s1, v0
	v_ashrrev_i32_e32 v9, 31, v8
	v_lshlrev_b64 v[36:37], 11, v[8:9]
	v_or_b32_e32 v36, v36, v7
	v_lshl_add_u64 v[8:9], s[64:65], 0, v[36:37]
	global_load_dwordx4 v[20:23], v[8:9], off nt
	v_or_b32_e32 v8, s1, v14
	v_ashrrev_i32_e32 v9, 31, v8
	v_lshlrev_b64 v[38:39], 11, v[8:9]
	v_or_b32_e32 v38, v38, v7
	v_lshl_add_u64 v[8:9], s[64:65], 0, v[38:39]
	global_load_dwordx4 v[24:27], v[8:9], off nt
	v_or_b32_e32 v8, s2, v0
	v_ashrrev_i32_e32 v9, 31, v8
	v_lshlrev_b64 v[40:41], 11, v[8:9]
	v_or_b32_e32 v40, v40, v7
	v_lshl_add_u64 v[8:9], s[64:65], 0, v[40:41]
	global_load_dwordx4 v[28:31], v[8:9], off nt
	v_or_b32_e32 v8, s2, v14
	v_ashrrev_i32_e32 v9, 31, v8
	v_lshlrev_b64 v[42:43], 11, v[8:9]
	v_or_b32_e32 v42, v42, v7
	v_lshl_add_u64 v[8:9], s[64:65], 0, v[42:43]
	global_load_dwordx4 v[32:35], v[8:9], off nt
	v_lshl_add_u32 v18, v0, 7, v6
	v_lshl_add_u32 v19, v14, 7, v6
	ds_read_b128 v[44:47], v18 offset:32768
	ds_read_b128 v[48:51], v19 offset:32768
	ds_read_b128 v[52:55], v18 offset:34816
	ds_read_b128 v[56:59], v19 offset:34816
	s_waitcnt vmcnt(3) lgkmcnt(3)
	v_lshlrev_b32_e32 v60, 16, v44
	v_and_b32_e32 v61, 0xffff0000, v44
	v_lshlrev_b32_e32 v62, 16, v20
	v_and_b32_e32 v63, 0xffff0000, v20
	v_lshlrev_b32_e32 v64, 16, v45
	v_and_b32_e32 v65, 0xffff0000, v45
	v_lshlrev_b32_e32 v66, 16, v21
	v_and_b32_e32 v67, 0xffff0000, v21
	v_lshlrev_b32_e32 v68, 16, v46
	v_and_b32_e32 v69, 0xffff0000, v46
	v_lshlrev_b32_e32 v70, 16, v22
	v_and_b32_e32 v71, 0xffff0000, v22
	v_lshlrev_b32_e32 v72, 16, v47
	v_and_b32_e32 v73, 0xffff0000, v47
	v_lshlrev_b32_e32 v74, 16, v23
	v_and_b32_e32 v75, 0xffff0000, v23
	v_pk_mul_f32 v[60:61], v[60:61], v[62:63]
	v_pk_mul_f32 v[64:65], v[64:65], v[66:67]
	v_pk_mul_f32 v[68:69], v[68:69], v[70:71]
	v_pk_mul_f32 v[72:73], v[72:73], v[74:75]
	v_cvt_pk_bf16_f32 v44, v60, v61
	v_cvt_pk_bf16_f32 v45, v64, v65
	v_cvt_pk_bf16_f32 v46, v68, v69
	v_cvt_pk_bf16_f32 v47, v72, v73
	v_lshl_add_u64 v[8:9], s[66:67], 0, v[36:37]
	global_store_dwordx4 v[8:9], v[44:47], off nt
	s_waitcnt vmcnt(3) lgkmcnt(2)
	v_lshlrev_b32_e32 v60, 16, v48
	v_and_b32_e32 v61, 0xffff0000, v48
	v_lshlrev_b32_e32 v62, 16, v24
	v_and_b32_e32 v63, 0xffff0000, v24
	v_lshlrev_b32_e32 v64, 16, v49
	v_and_b32_e32 v65, 0xffff0000, v49
	v_lshlrev_b32_e32 v66, 16, v25
	v_and_b32_e32 v67, 0xffff0000, v25
	v_lshlrev_b32_e32 v68, 16, v50
	v_and_b32_e32 v69, 0xffff0000, v50
	v_lshlrev_b32_e32 v70, 16, v26
	v_and_b32_e32 v71, 0xffff0000, v26
	v_lshlrev_b32_e32 v72, 16, v51
	v_and_b32_e32 v73, 0xffff0000, v51
	v_lshlrev_b32_e32 v74, 16, v27
	v_and_b32_e32 v75, 0xffff0000, v27
	v_pk_mul_f32 v[60:61], v[60:61], v[62:63]
	v_pk_mul_f32 v[64:65], v[64:65], v[66:67]
	v_pk_mul_f32 v[68:69], v[68:69], v[70:71]
	v_pk_mul_f32 v[72:73], v[72:73], v[74:75]
	v_cvt_pk_bf16_f32 v48, v60, v61
	v_cvt_pk_bf16_f32 v49, v64, v65
	v_cvt_pk_bf16_f32 v50, v68, v69
	v_cvt_pk_bf16_f32 v51, v72, v73
	v_lshl_add_u64 v[8:9], s[66:67], 0, v[38:39]
	global_store_dwordx4 v[8:9], v[48:51], off nt
	s_waitcnt vmcnt(3) lgkmcnt(1)
	v_lshlrev_b32_e32 v60, 16, v52
	v_and_b32_e32 v61, 0xffff0000, v52
	v_lshlrev_b32_e32 v62, 16, v28
	v_and_b32_e32 v63, 0xffff0000, v28
	v_lshlrev_b32_e32 v64, 16, v53
	v_and_b32_e32 v65, 0xffff0000, v53
	v_lshlrev_b32_e32 v66, 16, v29
	v_and_b32_e32 v67, 0xffff0000, v29
	v_lshlrev_b32_e32 v68, 16, v54
	v_and_b32_e32 v69, 0xffff0000, v54
	v_lshlrev_b32_e32 v70, 16, v30
	v_and_b32_e32 v71, 0xffff0000, v30
	v_lshlrev_b32_e32 v72, 16, v55
	v_and_b32_e32 v73, 0xffff0000, v55
	v_lshlrev_b32_e32 v74, 16, v31
	v_and_b32_e32 v75, 0xffff0000, v31
	v_pk_mul_f32 v[60:61], v[60:61], v[62:63]
	v_pk_mul_f32 v[64:65], v[64:65], v[66:67]
	v_pk_mul_f32 v[68:69], v[68:69], v[70:71]
	v_pk_mul_f32 v[72:73], v[72:73], v[74:75]
	v_cvt_pk_bf16_f32 v52, v60, v61
	v_cvt_pk_bf16_f32 v53, v64, v65
	v_cvt_pk_bf16_f32 v54, v68, v69
	v_cvt_pk_bf16_f32 v55, v72, v73
	v_lshl_add_u64 v[8:9], s[66:67], 0, v[40:41]
	global_store_dwordx4 v[8:9], v[52:55], off nt
	s_waitcnt vmcnt(3) lgkmcnt(0)
	v_lshlrev_b32_e32 v60, 16, v56
	v_and_b32_e32 v61, 0xffff0000, v56
	v_lshlrev_b32_e32 v62, 16, v32
	v_and_b32_e32 v63, 0xffff0000, v32
	v_lshlrev_b32_e32 v64, 16, v57
	v_and_b32_e32 v65, 0xffff0000, v57
	v_lshlrev_b32_e32 v66, 16, v33
	v_and_b32_e32 v67, 0xffff0000, v33
	v_lshlrev_b32_e32 v68, 16, v58
	v_and_b32_e32 v69, 0xffff0000, v58
	v_lshlrev_b32_e32 v70, 16, v34
	v_and_b32_e32 v71, 0xffff0000, v34
	v_lshlrev_b32_e32 v72, 16, v59
	v_and_b32_e32 v73, 0xffff0000, v59
	v_lshlrev_b32_e32 v74, 16, v35
	v_and_b32_e32 v75, 0xffff0000, v35
	v_pk_mul_f32 v[60:61], v[60:61], v[62:63]
	v_pk_mul_f32 v[64:65], v[64:65], v[66:67]
	v_pk_mul_f32 v[68:69], v[68:69], v[70:71]
	v_pk_mul_f32 v[72:73], v[72:73], v[74:75]
	v_cvt_pk_bf16_f32 v56, v60, v61
	v_cvt_pk_bf16_f32 v57, v64, v65
	v_cvt_pk_bf16_f32 v58, v68, v69
	v_cvt_pk_bf16_f32 v59, v72, v73
	v_lshl_add_u64 v[8:9], s[66:67], 0, v[42:43]
	global_store_dwordx4 v[8:9], v[56:59], off nt

.LBB0_533:
	s_add_i32 s20, s31, s83
	s_add_i32 s20, s20, -2
	s_cmp_lt_i32 s0, s34
	s_cselect_b64 s[0:1], -1, 0
	s_cmp_le_u32 s68, s20
	s_cselect_b64 s[10:11], -1, 0
	s_or_b64 s[10:11], s[8:9], s[10:11]
	s_cmp_le_u32 s20, s74
	s_cselect_b64 s[12:13], -1, 0
	s_and_b64 s[10:11], s[10:11], s[12:13]
	s_and_b64 s[12:13], s[0:1], s[10:11]
	s_andn2_b64 vcc, exec, s[12:13]
	s_cbranch_vccz .Lna_win
	s_xor_b64 s[0:1], s[0:1], -1
	s_or_b64 s[10:11], s[0:1], s[10:11]
	s_and_b64 vcc, exec, s[10:11]
	s_cbranch_vccz .Lna_next
	s_and_b32 s10, s51, 0xc000
	s_add_i32 s10, s10, 0
	v_add_u32_e32 v0, s10, v235
	v_add_u32_e32 v2, v0, v241
	ds_read_b128 v[80:83], v2
	ds_read_b128 v[84:87], v2 offset:4096
	v_add_u32_e32 v2, v0, v242
	ds_read_b128 v[88:91], v2
	ds_read_b128 v[92:95], v2 offset:4096
	v_add_u32_e32 v2, v0, v243
	v_add_u32_e32 v0, v0, v244
	ds_read_b128 v[96:99], v2
	ds_read_b128 v[100:103], v2 offset:4096
	ds_read_b128 v[104:107], v0
	ds_read_b128 v[108:111], v0 offset:4096
	v_add_u32_e32 v0, s10, v238
	ds_read_b64_tr_b16 v[192:193], v0 offset:8192
	ds_read_b64_tr_b16 v[194:195], v0 offset:8704
	ds_read_b64_tr_b16 v[10:11], v0 offset:9216
	ds_read_b64_tr_b16 v[12:13], v0 offset:9728
	ds_read_b64_tr_b16 v[6:7], v0 offset:10240
	ds_read_b64_tr_b16 v[8:9], v0 offset:10752
	ds_read_b64_tr_b16 v[2:3], v0 offset:11264
	ds_read_b64_tr_b16 v[4:5], v0 offset:11776
	s_setprio 1
	s_waitcnt lgkmcnt(14)
	v_mfma_f32_32x32x16_bf16 v[144:159], v[80:83], v[188:191], v[64:79]
	v_mfma_f32_32x32x16_bf16 v[128:143], v[84:87], v[188:191], v[64:79]
	s_waitcnt lgkmcnt(13)
	v_mfma_f32_32x32x16_bf16 v[144:159], v[88:91], v[184:187], v[144:159]
	s_waitcnt lgkmcnt(12)
	v_mfma_f32_32x32x16_bf16 v[128:143], v[92:95], v[184:187], v[128:143]
	s_waitcnt lgkmcnt(11)
	v_mfma_f32_32x32x16_bf16 v[144:159], v[96:99], v[180:183], v[144:159]
	s_waitcnt lgkmcnt(10)
	v_mfma_f32_32x32x16_bf16 v[128:143], v[100:103], v[180:183], v[128:143]
	s_waitcnt lgkmcnt(9)
	v_mfma_f32_32x32x16_bf16 v[144:159], v[104:107], v[176:179], v[144:159]
	s_waitcnt lgkmcnt(8)
	v_mfma_f32_32x32x16_bf16 v[128:143], v[108:111], v[176:179], v[128:143]
	s_setprio 0
	v_max3_f32 v14, v144, v145, v146
	v_max3_f32 v15, v147, v148, v149
	v_max3_f32 v80, v150, v151, v152
	v_max3_f32 v81, v153, v154, v155
	v_max3_f32 v82, v156, v157, v158
	v_max3_f32 v83, v128, v129, v130
	v_max3_f32 v84, v131, v132, v133
	v_max3_f32 v85, v134, v135, v136
	s_nop 0
	v_max3_f32 v14, v14, v15, v80
	v_max3_f32 v86, v137, v138, v139
	v_max3_f32 v15, v81, v82, v159
	v_max3_f32 v87, v140, v141, v142
	s_xor_b64 s[10:11], s[46:47], -1
	v_max3_f32 v80, v83, v84, v85
	v_max3_f32 v81, v86, v87, v143
	s_nop 0
	v_max3_f32 v14, v14, v15, v80
	v_max_f32_e32 v15, v81, v81
	v_max_f32_e32 v14, v14, v14
	v_and_b32_e32 v80, 64, v211
	v_max_f32_e32 v14, v14, v15
	v_xor_b32_e32 v15, 32, v211
	v_add_u32_e32 v80, 64, v80
	v_cmp_lt_i32_e32 vcc, v15, v80
	s_nop 1
	v_cndmask_b32_e32 v15, v211, v15, vcc
	v_lshlrev_b32_e32 v15, 2, v15
	ds_bpermute_b32 v15, v15, v14
	s_waitcnt lgkmcnt(0)
	v_max_f32_e32 v15, v15, v15
	v_max_f32_e32 v14, v14, v15
	v_cmp_lt_f32_e32 vcc, s27, v14
	s_or_b64 s[10:11], vcc, s[10:11]
	v_cndmask_b32_e64 v15, 0, 1, s[10:11]
	v_cmp_ne_u32_e32 vcc, 0, v15
	s_cbranch_vccz .Lna_547
	v_max_f32_e32 v15, v14, v14
	v_max_f32_e32 v15, 0, v15
	v_cndmask_b32_e64 v80, v14, v15, s[46:47]
	v_exp_f32_e64 v15, -v80
	v_add_f32_e32 v212, v212, v80
	v_xor_b32_e32 v64, 0x80000000, v212
	v_pk_add_f32 v[144:145], v[144:145], v[80:81] op_sel_hi:[1,0] neg_lo:[0,1] neg_hi:[0,1]
	v_cndmask_b32_e64 v160, 0, v15, s[46:47]
	v_pk_add_f32 v[128:129], v[128:129], v[80:81] op_sel_hi:[1,0] neg_lo:[0,1] neg_hi:[0,1]
	v_pk_add_f32 v[146:147], v[146:147], v[80:81] op_sel_hi:[1,0] neg_lo:[0,1] neg_hi:[0,1]
	v_pk_add_f32 v[130:131], v[130:131], v[80:81] op_sel_hi:[1,0] neg_lo:[0,1] neg_hi:[0,1]
	v_pk_add_f32 v[148:149], v[148:149], v[80:81] op_sel_hi:[1,0] neg_lo:[0,1] neg_hi:[0,1]
	v_pk_add_f32 v[132:133], v[132:133], v[80:81] op_sel_hi:[1,0] neg_lo:[0,1] neg_hi:[0,1]
	v_pk_add_f32 v[150:151], v[150:151], v[80:81] op_sel_hi:[1,0] neg_lo:[0,1] neg_hi:[0,1]
	v_pk_add_f32 v[134:135], v[134:135], v[80:81] op_sel_hi:[1,0] neg_lo:[0,1] neg_hi:[0,1]
	v_pk_add_f32 v[152:153], v[152:153], v[80:81] op_sel_hi:[1,0] neg_lo:[0,1] neg_hi:[0,1]
	v_pk_add_f32 v[136:137], v[136:137], v[80:81] op_sel_hi:[1,0] neg_lo:[0,1] neg_hi:[0,1]
	v_pk_add_f32 v[154:155], v[154:155], v[80:81] op_sel_hi:[1,0] neg_lo:[0,1] neg_hi:[0,1]
	v_pk_add_f32 v[138:139], v[138:139], v[80:81] op_sel_hi:[1,0] neg_lo:[0,1] neg_hi:[0,1]
	v_pk_add_f32 v[156:157], v[156:157], v[80:81] op_sel_hi:[1,0] neg_lo:[0,1] neg_hi:[0,1]
	v_pk_add_f32 v[140:141], v[140:141], v[80:81] op_sel_hi:[1,0] neg_lo:[0,1] neg_hi:[0,1]
	v_pk_add_f32 v[158:159], v[158:159], v[80:81] op_sel_hi:[1,0] neg_lo:[0,1] neg_hi:[0,1]
	v_pk_add_f32 v[142:143], v[142:143], v[80:81] op_sel_hi:[1,0] neg_lo:[0,1] neg_hi:[0,1]
	v_pk_mul_f32 v[30:31], v[30:31], v[160:161] op_sel_hi:[1,0]
	v_pk_mul_f32 v[28:29], v[28:29], v[160:161] op_sel_hi:[1,0]
	v_pk_mul_f32 v[26:27], v[26:27], v[160:161] op_sel_hi:[1,0]
	v_pk_mul_f32 v[24:25], v[24:25], v[160:161] op_sel_hi:[1,0]
	v_pk_mul_f32 v[22:23], v[22:23], v[160:161] op_sel_hi:[1,0]
	v_pk_mul_f32 v[20:21], v[20:21], v[160:161] op_sel_hi:[1,0]
	v_pk_mul_f32 v[18:19], v[18:19], v[160:161] op_sel_hi:[1,0]
	v_pk_mul_f32 v[16:17], v[16:17], v[160:161] op_sel_hi:[1,0]
	v_pk_mul_f32 v[46:47], v[46:47], v[160:161] op_sel_hi:[1,0]
	v_pk_mul_f32 v[44:45], v[44:45], v[160:161] op_sel_hi:[1,0]
	v_pk_mul_f32 v[42:43], v[42:43], v[160:161] op_sel_hi:[1,0]
	v_pk_mul_f32 v[40:41], v[40:41], v[160:161] op_sel_hi:[1,0]
	v_pk_mul_f32 v[38:39], v[38:39], v[160:161] op_sel_hi:[1,0]
	v_pk_mul_f32 v[36:37], v[36:37], v[160:161] op_sel_hi:[1,0]
	v_pk_mul_f32 v[34:35], v[34:35], v[160:161] op_sel_hi:[1,0]
	v_pk_mul_f32 v[32:33], v[32:33], v[160:161] op_sel_hi:[1,0]
	v_mov_b32_e32 v65, v64
	v_mov_b32_e32 v66, v64
	v_mov_b32_e32 v67, v64
	v_mov_b32_e32 v68, v64
	v_mov_b32_e32 v69, v64
	v_mov_b32_e32 v70, v64
	v_mov_b32_e32 v71, v64
	v_mov_b32_e32 v72, v64
	v_mov_b32_e32 v73, v64
	v_mov_b32_e32 v74, v64
	v_mov_b32_e32 v75, v64
	v_mov_b32_e32 v76, v64
	v_mov_b32_e32 v77, v64
	v_mov_b32_e32 v78, v64
	v_mov_b32_e32 v79, v64
	v_pk_mul_f32 v[62:63], v[62:63], v[160:161] op_sel_hi:[1,0]
	v_pk_mul_f32 v[60:61], v[60:61], v[160:161] op_sel_hi:[1,0]
	v_pk_mul_f32 v[58:59], v[58:59], v[160:161] op_sel_hi:[1,0]
	v_pk_mul_f32 v[56:57], v[56:57], v[160:161] op_sel_hi:[1,0]
	v_pk_mul_f32 v[54:55], v[54:55], v[160:161] op_sel_hi:[1,0]
	v_pk_mul_f32 v[52:53], v[52:53], v[160:161] op_sel_hi:[1,0]
	v_pk_mul_f32 v[50:51], v[50:51], v[160:161] op_sel_hi:[1,0]
	v_pk_mul_f32 v[48:49], v[48:49], v[160:161] op_sel_hi:[1,0]
	s_or_b64 s[46:47], s[46:47], exec
.Lna_547:
	v_exp_f32_e32 v15, v144
	v_exp_f32_e32 v144, v128
	v_exp_f32_e32 v128, v145
	v_exp_f32_e32 v129, v129
	v_exp_f32_e32 v145, v146
	v_exp_f32_e32 v130, v130
	v_exp_f32_e32 v146, v147
	v_exp_f32_e32 v131, v131
	v_exp_f32_e32 v147, v148
	v_exp_f32_e32 v148, v132
	v_exp_f32_e32 v149, v149
	v_exp_f32_e32 v218, v133
	v_exp_f32_e32 v150, v150
	v_exp_f32_e32 v219, v134
	v_exp_f32_e32 v151, v151
	v_exp_f32_e32 v220, v135
	v_exp_f32_e32 v132, v152
	v_exp_f32_e32 v133, v136
	v_exp_f32_e32 v134, v153
	v_exp_f32_e32 v135, v137
	v_exp_f32_e32 v137, v154
	v_exp_f32_e32 v138, v138
	v_exp_f32_e32 v152, v155
	v_exp_f32_e32 v139, v139
	v_exp_f32_e32 v153, v156
	v_exp_f32_e32 v154, v140
	v_exp_f32_e32 v155, v157
	v_exp_f32_e32 v156, v141
	v_exp_f32_e32 v157, v158
	v_exp_f32_e32 v158, v142
	v_exp_f32_e32 v159, v159
	v_exp_f32_e32 v143, v143
	v_cvt_pk_bf16_f32 v128, v15, v128
	v_cvt_pk_bf16_f32 v132, v132, v134
	v_cvt_pk_bf16_f32 v136, v144, v129
	v_cvt_pk_bf16_f32 v140, v133, v135
	v_cvt_pk_bf16_f32 v129, v145, v146
	v_cvt_pk_bf16_f32 v133, v137, v152
	v_cvt_pk_bf16_f32 v137, v130, v131
	v_cvt_pk_bf16_f32 v141, v138, v139
	v_cvt_pk_bf16_f32 v130, v147, v149
	v_cvt_pk_bf16_f32 v134, v153, v155
	v_cvt_pk_bf16_f32 v138, v148, v218
	v_cvt_pk_bf16_f32 v142, v154, v156
	v_cvt_pk_bf16_f32 v131, v150, v151
	v_cvt_pk_bf16_f32 v135, v157, v159
	v_cvt_pk_bf16_f32 v139, v219, v220
	v_cvt_pk_bf16_f32 v143, v158, v143
	ds_read_b64_tr_b16 v[144:145], v0 offset:12288
	ds_read_b64_tr_b16 v[146:147], v0 offset:12800
	ds_read_b64_tr_b16 v[148:149], v0 offset:13312
	ds_read_b64_tr_b16 v[150:151], v0 offset:13824
	ds_read_b64_tr_b16 v[152:153], v0 offset:14336
	ds_read_b64_tr_b16 v[154:155], v0 offset:14848
	ds_read_b64_tr_b16 v[156:157], v0 offset:15360
	ds_read_b64_tr_b16 v[158:159], v0 offset:15872
	s_setprio 1
	v_mfma_f32_32x32x16_bf16 v[16:31], v[192:195], v[128:131], v[16:31]
	s_mov_b32 s61, s60
	s_mov_b32 s62, s60
	s_mov_b32 s63, s60
	v_mfma_f32_32x32x16_bf16 v[16:31], v[10:13], v[132:135], v[16:31]
	v_mfma_f32_32x32x16_bf16 v[16:31], v[6:9], v[136:139], v[16:31]
	v_mfma_f32_32x32x16_bf16 v[16:31], v[2:5], v[140:143], v[16:31]
	v_mov_b64_e32 v[2:3], s[60:61]
	v_mov_b64_e32 v[4:5], s[62:63]
	s_waitcnt lgkmcnt(6)
	v_mfma_f32_32x32x16_bf16 v[32:47], v[144:147], v[128:131], v[32:47]
	v_mfma_f32_32x32x16_bf16 v[48:63], v[2:5], v[128:131], v[48:63]
	s_waitcnt lgkmcnt(4)
	v_mfma_f32_32x32x16_bf16 v[32:47], v[148:151], v[132:135], v[32:47]
	v_mfma_f32_32x32x16_bf16 v[48:63], v[2:5], v[132:135], v[48:63]
	s_waitcnt lgkmcnt(2)
	v_mfma_f32_32x32x16_bf16 v[32:47], v[152:155], v[136:139], v[32:47]
	v_mfma_f32_32x32x16_bf16 v[48:63], v[2:5], v[136:139], v[48:63]
	s_waitcnt lgkmcnt(0)
	v_mfma_f32_32x32x16_bf16 v[32:47], v[156:159], v[140:143], v[32:47]
	v_mfma_f32_32x32x16_bf16 v[48:63], v[2:5], v[140:143], v[48:63]
	s_setprio 0
	s_branch .Lna_next

.Lna_541:
	v_exp_f32_e32 v0, v14
	v_exp_f32_e32 v14, v15
	v_exp_f32_e32 v15, v80
	v_exp_f32_e32 v81, v81
	v_exp_f32_e32 v82, v82
	v_exp_f32_e32 v83, v83
	v_exp_f32_e32 v94, v84
	v_exp_f32_e32 v95, v85
	v_exp_f32_e32 v84, v86
	v_exp_f32_e32 v85, v87
	v_exp_f32_e32 v86, v88
	v_exp_f32_e32 v87, v89
	v_exp_f32_e32 v88, v90
	v_exp_f32_e32 v89, v91
	v_exp_f32_e32 v90, v92
	v_exp_f32_e32 v91, v93
	v_cvt_pk_bf16_f32 v80, v0, v14
	v_cvt_pk_bf16_f32 v84, v84, v85
	v_cvt_pk_bf16_f32 v81, v15, v81
	v_cvt_pk_bf16_f32 v85, v86, v87
	v_cvt_pk_bf16_f32 v82, v82, v83
	v_cvt_pk_bf16_f32 v86, v88, v89
	v_cvt_pk_bf16_f32 v83, v94, v95
	v_cvt_pk_bf16_f32 v87, v90, v91
	s_setprio 1
	v_mfma_f32_32x32x16_bf16 v[32:47], v[10:13], v[80:83], v[32:47]
	s_mov_b32 s61, s60
	s_mov_b32 s62, s60
	s_mov_b32 s63, s60
	v_mfma_f32_32x32x16_bf16 v[32:47], v[6:9], v[84:87], v[32:47]
	v_mov_b64_e32 v[6:7], s[60:61]
	v_mov_b64_e32 v[8:9], s[62:63]
	v_mfma_f32_32x32x16_bf16 v[16:31], v[96:99], v[80:83], v[16:31]
	s_nop 3
	v_mfma_f32_32x32x16_bf16 v[48:63], v[6:9], v[80:83], v[48:63]
	v_mfma_f32_32x32x16_bf16 v[48:63], v[6:9], v[84:87], v[48:63]
	v_mfma_f32_32x32x16_bf16 v[16:31], v[2:5], v[84:87], v[16:31]
	s_setprio 0
.Lna_next:
	s_add_i32 s83, s83, 1
	s_addk_i32 s51, 0x4000
	s_add_i32 s50, s50, 64
	s_add_i32 s0, s86, s83
	s_cmp_lg_u32 s0, 2
	s_cbranch_scc1 .LBB0_528
	s_nop 15
	v_mov_b64_e32 v[80:81], v[16:17]
	v_mov_b64_e32 v[82:83], v[18:19]
	v_mov_b64_e32 v[84:85], v[20:21]
	v_mov_b64_e32 v[86:87], v[22:23]
	v_mov_b64_e32 v[88:89], v[24:25]
	v_mov_b64_e32 v[90:91], v[26:27]
	v_mov_b64_e32 v[92:93], v[28:29]
	v_mov_b64_e32 v[94:95], v[30:31]
	v_mov_b64_e32 v[96:97], v[32:33]
	v_mov_b64_e32 v[98:99], v[34:35]
	v_mov_b64_e32 v[100:101], v[36:37]
	v_mov_b64_e32 v[102:103], v[38:39]
	v_mov_b64_e32 v[104:105], v[40:41]
	v_mov_b64_e32 v[106:107], v[42:43]
	v_mov_b64_e32 v[108:109], v[44:45]
	v_mov_b64_e32 v[110:111], v[46:47]
	v_mov_b32_e32 v160, v48
	s_branch .LBB0_489
